# diff-attention unit epilogue: permlane32_swap pairs + 8 dwordx4 stores instead of 16 dwordx2; all gamma loads issued up front
# speedup vs baseline: 1.0158x; 1.0047x over previous
; #define LAS __attribute__((address_space(3)))
; template <bool DIFF> ...
;     ...
;     if (DIFF) {
;         __syncthreads();
;         LAS float* ex = (LAS float*)lds + (wid & 3) * 4096;
;         if (c == 1) { const float f = inv * lam;
; #pragma unroll
;             for (int i = 0; i < 4; ++i)
; #pragma unroll
;                 for (int r = 0; r < 16; ++r) ex[(i * 16 + r) * 64 + lane] = o[i][r] * f; }
;         __syncthreads();
;         if (c == 0) {
;             float ss = 0.f;
; #pragma unroll
;             for (int i = 0; i < 4; ++i)
; #pragma unroll
;                 for (int r = 0; r < 16; ++r) { const float v = o[i][r] * inv - ex[(i * 16 + r) * 64 + lane]; o[i][r] = v; ss += v * v; }
;             ss += __shfl_xor(ss, 32);
;             const float rstd = rsqrtf(ss * (1.f / 128.f) + 1e-6f) * oscale;
.LBB0_123:
	s_cmpk_gt_u32 s26, 0xff
	s_waitcnt lgkmcnt(0)
	s_barrier
	s_cbranch_scc1 .LBB0_110
	ds_read2st64_b32 v[66:67], v0 offset1:1
	ds_read2st64_b32 v[68:69], v0 offset0:2 offset1:3
	ds_read2st64_b32 v[76:77], v0 offset0:4 offset1:5
	ds_read2st64_b32 v[78:79], v0 offset0:6 offset1:7
	ds_read2st64_b32 v[80:81], v0 offset0:8 offset1:9
	ds_read2st64_b32 v[82:83], v0 offset0:10 offset1:11
	ds_read2st64_b32 v[84:85], v0 offset0:12 offset1:13
	ds_read2st64_b32 v[86:87], v0 offset0:14 offset1:15
	ds_read2st64_b32 v[88:89], v0 offset0:16 offset1:17
	ds_read2st64_b32 v[114:115], v0 offset0:18 offset1:19
	ds_read2st64_b32 v[116:117], v0 offset0:20 offset1:21
	ds_read2st64_b32 v[118:119], v0 offset0:22 offset1:23
	ds_read2st64_b32 v[120:121], v0 offset0:24 offset1:25
	ds_read2st64_b32 v[122:123], v0 offset0:26 offset1:27
	ds_read2st64_b32 v[124:125], v0 offset0:28 offset1:29
	ds_read2st64_b32 v[126:127], v0 offset0:30 offset1:31
	ds_read2st64_b32 v[128:129], v0 offset0:32 offset1:33
	ds_read2st64_b32 v[130:131], v0 offset0:34 offset1:35
	ds_read2st64_b32 v[132:133], v0 offset0:36 offset1:37
	ds_read2st64_b32 v[134:135], v0 offset0:38 offset1:39
	ds_read2st64_b32 v[136:137], v0 offset0:40 offset1:41
	ds_read2st64_b32 v[138:139], v0 offset0:42 offset1:43
	ds_read2st64_b32 v[140:141], v0 offset0:44 offset1:45
	ds_read2st64_b32 v[142:143], v0 offset0:46 offset1:47
	ds_read2st64_b32 v[112:113], v0 offset0:56 offset1:57
	ds_read2st64_b32 v[144:145], v0 offset0:58 offset1:59
	ds_read2st64_b32 v[70:71], v0 offset0:60 offset1:61
	ds_read2st64_b32 v[72:73], v0 offset0:62 offset1:63
	ds_read2st64_b32 v[146:147], v0 offset0:48 offset1:49
	ds_read2st64_b32 v[148:149], v0 offset0:50 offset1:51
	ds_read2st64_b32 v[150:151], v0 offset0:52 offset1:53
	ds_read2st64_b32 v[152:153], v0 offset0:54 offset1:55
	s_waitcnt lgkmcnt(14)
	v_pk_fma_f32 v[94:95], v[50:51], v[74:75], v[66:67] op_sel_hi:[1,0,1] neg_lo:[0,0,1] neg_hi:[0,0,1]
	v_pk_fma_f32 v[90:91], v[52:53], v[74:75], v[68:69] op_sel_hi:[1,0,1] neg_lo:[0,0,1] neg_hi:[0,0,1]
	v_pk_mul_f32 v[156:157], v[94:95], v[94:95]
	v_lshlrev_b32_e32 v163, 2, v184
	v_pk_mul_f32 v[154:155], v[90:91], v[90:91]
	s_waitcnt lgkmcnt(7)
	v_pk_fma_f32 v[10:11], v[10:11], v[74:75], v[112:113] op_sel_hi:[1,0,1] neg_lo:[0,0,1] neg_hi:[0,0,1]
	v_add_f32_e32 v112, v156, v157
	global_load_dwordx4 v[66:69], v163, s[10:11]
	global_load_dwordx4 v[50:53], v163, s[10:11] offset:32
	v_pk_fma_f32 v[104:105], v[54:55], v[74:75], v[76:77] op_sel_hi:[1,0,1] neg_lo:[0,0,1] neg_hi:[0,0,1]
	v_add_f32_e32 v112, v112, v154
	v_pk_mul_f32 v[160:161], v[104:105], v[104:105]
	v_add_f32_e32 v112, v112, v155
	v_pk_fma_f32 v[96:97], v[56:57], v[74:75], v[78:79] op_sel_hi:[1,0,1] neg_lo:[0,0,1] neg_hi:[0,0,1]
	v_add_f32_e32 v112, v112, v160
	v_pk_mul_f32 v[158:159], v[96:97], v[96:97]
	v_add_f32_e32 v112, v112, v161
	v_pk_fma_f32 v[108:109], v[58:59], v[74:75], v[80:81] op_sel_hi:[1,0,1] neg_lo:[0,0,1] neg_hi:[0,0,1]
	v_add_f32_e32 v112, v112, v158
	v_pk_mul_f32 v[168:169], v[108:109], v[108:109]
	v_add_f32_e32 v112, v112, v159
	s_or_b32 s0, s25, s35
	v_pk_fma_f32 v[102:103], v[60:61], v[74:75], v[82:83] op_sel_hi:[1,0,1] neg_lo:[0,0,1] neg_hi:[0,0,1]
	v_add_f32_e32 v112, v112, v168
	s_ashr_i32 s1, s0, 31
	v_pk_mul_f32 v[166:167], v[102:103], v[102:103]
	v_add_f32_e32 v112, v112, v169
	s_lshl_b64 s[0:1], s[0:1], 11
	v_readlane_b32 s2, v248, 8
	global_load_dwordx4 v[58:61], v163, s[10:11] offset:64
	global_load_dwordx4 v[54:57], v163, s[10:11] offset:96
	v_pk_fma_f32 v[110:111], v[62:63], v[74:75], v[84:85] op_sel_hi:[1,0,1] neg_lo:[0,0,1] neg_hi:[0,0,1]
	v_add_f32_e32 v112, v112, v166
	s_add_u32 s0, s2, s0
	v_readlane_b32 s2, v248, 9
	v_pk_mul_f32 v[198:199], v[110:111], v[110:111]
	v_add_f32_e32 v112, v112, v167
	s_addc_u32 s1, s2, s1
	v_lshlrev_b32_e32 v0, 11, v183
	v_pk_fma_f32 v[106:107], v[64:65], v[74:75], v[86:87] op_sel_hi:[1,0,1] neg_lo:[0,0,1] neg_hi:[0,0,1]
	v_add_f32_e32 v112, v112, v198
	v_lshl_add_u64 v[100:101], s[0:1], 0, v[0:1]
	v_lshlrev_b32_e32 v0, 2, v184
	v_pk_mul_f32 v[184:185], v[106:107], v[106:107]
	v_add_f32_e32 v112, v112, v199
	v_pk_fma_f32 v[64:65], v[34:35], v[74:75], v[88:89] op_sel_hi:[1,0,1] neg_lo:[0,0,1] neg_hi:[0,0,1]
	v_add_f32_e32 v112, v112, v184
	v_pk_mul_f32 v[200:201], v[64:65], v[64:65]
	v_add_f32_e32 v112, v112, v185
	v_pk_fma_f32 v[62:63], v[36:37], v[74:75], v[114:115] op_sel_hi:[1,0,1] neg_lo:[0,0,1] neg_hi:[0,0,1]
	v_add_f32_e32 v112, v112, v200
	v_pk_mul_f32 v[114:115], v[62:63], v[62:63]
	v_add_f32_e32 v112, v112, v201
	v_pk_fma_f32 v[80:81], v[38:39], v[74:75], v[116:117] op_sel_hi:[1,0,1] neg_lo:[0,0,1] neg_hi:[0,0,1]
	v_add_f32_e32 v112, v112, v114
	v_pk_mul_f32 v[116:117], v[80:81], v[80:81]
	v_add_f32_e32 v112, v112, v115
	v_pk_fma_f32 v[76:77], v[40:41], v[74:75], v[118:119] op_sel_hi:[1,0,1] neg_lo:[0,0,1] neg_hi:[0,0,1]
	v_add_f32_e32 v112, v112, v116
	v_pk_mul_f32 v[118:119], v[76:77], v[76:77]
	v_add_f32_e32 v112, v112, v117
	v_pk_fma_f32 v[82:83], v[42:43], v[74:75], v[120:121] op_sel_hi:[1,0,1] neg_lo:[0,0,1] neg_hi:[0,0,1]
	v_add_f32_e32 v112, v112, v118
	v_pk_mul_f32 v[120:121], v[82:83], v[82:83]
	v_add_f32_e32 v112, v112, v119
	v_pk_fma_f32 v[78:79], v[44:45], v[74:75], v[122:123] op_sel_hi:[1,0,1] neg_lo:[0,0,1] neg_hi:[0,0,1]
	v_add_f32_e32 v112, v112, v120
	v_pk_mul_f32 v[122:123], v[78:79], v[78:79]
	v_add_f32_e32 v112, v112, v121
	v_pk_fma_f32 v[86:87], v[46:47], v[74:75], v[124:125] op_sel_hi:[1,0,1] neg_lo:[0,0,1] neg_hi:[0,0,1]
	v_add_f32_e32 v112, v112, v122
	v_pk_mul_f32 v[124:125], v[86:87], v[86:87]
	v_add_f32_e32 v112, v112, v123
; template <bool DIFF> ...
;     ...
;             float ss = 0.f;
; #pragma unroll
;             for (int i = 0; i < 4; ++i)
; #pragma unroll
;                 for (int r = 0; r < 16; ++r) { const float v = o[i][r] * inv - ex[(i * 16 + r) * 64 + lane]; o[i][r] = v; ss += v * v; }
;             ss += __shfl_xor(ss, 32);
;             const float rstd = rsqrtf(ss * (1.f / 128.f) + 1e-6f) * oscale;
;             bf16_t* orow = Op + (size_t)(qr + l32) * opitch;
; #pragma unroll
;             for (int i = 0; i < 4; ++i)
; #pragma unroll
;                 for (int r4 = 0; r4 < 4; ++r4) { const int dv = i * 32 + r4 * 8 + hi * 4; const f32x4 gg = *(const f32x4*)(subg + dv); u32x2 w;
	v_pk_fma_f32 v[84:85], v[48:49], v[74:75], v[126:127] op_sel_hi:[1,0,1] neg_lo:[0,0,1] neg_hi:[0,0,1]
	v_add_f32_e32 v112, v112, v124
	v_pk_mul_f32 v[126:127], v[84:85], v[84:85]
	v_add_f32_e32 v112, v112, v125
	v_pk_fma_f32 v[88:89], v[18:19], v[74:75], v[128:129] op_sel_hi:[1,0,1] neg_lo:[0,0,1] neg_hi:[0,0,1]
	v_add_f32_e32 v112, v112, v126
	v_pk_mul_f32 v[128:129], v[88:89], v[88:89]
	v_add_f32_e32 v112, v112, v127
	v_pk_fma_f32 v[20:21], v[20:21], v[74:75], v[130:131] op_sel_hi:[1,0,1] neg_lo:[0,0,1] neg_hi:[0,0,1]
	v_add_f32_e32 v112, v112, v128
	v_pk_mul_f32 v[130:131], v[20:21], v[20:21]
	v_add_f32_e32 v112, v112, v129
	v_pk_fma_f32 v[18:19], v[24:25], v[74:75], v[134:135] op_sel_hi:[1,0,1] neg_lo:[0,0,1] neg_hi:[0,0,1]
	v_pk_fma_f32 v[24:25], v[22:23], v[74:75], v[132:133] op_sel_hi:[1,0,1] neg_lo:[0,0,1] neg_hi:[0,0,1]
	v_add_f32_e32 v112, v112, v130
	v_pk_mul_f32 v[132:133], v[24:25], v[24:25]
	v_add_f32_e32 v112, v112, v131
	v_add_f32_e32 v112, v112, v132
	v_pk_mul_f32 v[134:135], v[18:19], v[18:19]
	v_add_f32_e32 v112, v112, v133
	v_pk_fma_f32 v[22:23], v[28:29], v[74:75], v[138:139] op_sel_hi:[1,0,1] neg_lo:[0,0,1] neg_hi:[0,0,1]
	v_pk_fma_f32 v[28:29], v[26:27], v[74:75], v[136:137] op_sel_hi:[1,0,1] neg_lo:[0,0,1] neg_hi:[0,0,1]
	v_add_f32_e32 v112, v112, v134
	v_pk_mul_f32 v[136:137], v[28:29], v[28:29]
	v_add_f32_e32 v112, v112, v135
	v_add_f32_e32 v112, v112, v136
	v_pk_mul_f32 v[138:139], v[22:23], v[22:23]
	v_add_f32_e32 v112, v112, v137
	v_pk_fma_f32 v[30:31], v[30:31], v[74:75], v[140:141] op_sel_hi:[1,0,1] neg_lo:[0,0,1] neg_hi:[0,0,1]
	v_add_f32_e32 v112, v112, v138
	v_pk_mul_f32 v[140:141], v[30:31], v[30:31]
	v_add_f32_e32 v112, v112, v139
	v_pk_fma_f32 v[26:27], v[32:33], v[74:75], v[142:143] op_sel_hi:[1,0,1] neg_lo:[0,0,1] neg_hi:[0,0,1]
	v_add_f32_e32 v112, v112, v140
	v_pk_mul_f32 v[142:143], v[26:27], v[26:27]
	v_add_f32_e32 v112, v112, v141
	s_waitcnt lgkmcnt(3)
	v_pk_fma_f32 v[32:33], v[2:3], v[74:75], v[146:147] op_sel_hi:[1,0,1] neg_lo:[0,0,1] neg_hi:[0,0,1]
	v_add_f32_e32 v112, v112, v142
	v_pk_mul_f32 v[146:147], v[32:33], v[32:33]
	v_add_f32_e32 v112, v112, v143
	s_waitcnt lgkmcnt(2)
	v_pk_fma_f32 v[4:5], v[4:5], v[74:75], v[148:149] op_sel_hi:[1,0,1] neg_lo:[0,0,1] neg_hi:[0,0,1]
	v_add_f32_e32 v112, v112, v146
	v_pk_mul_f32 v[148:149], v[4:5], v[4:5]
	v_add_f32_e32 v112, v112, v147
	s_waitcnt lgkmcnt(0)
	v_pk_fma_f32 v[2:3], v[8:9], v[74:75], v[152:153] op_sel_hi:[1,0,1] neg_lo:[0,0,1] neg_hi:[0,0,1]
	v_pk_fma_f32 v[8:9], v[6:7], v[74:75], v[150:151] op_sel_hi:[1,0,1] neg_lo:[0,0,1] neg_hi:[0,0,1]
	v_add_f32_e32 v112, v112, v148
	v_pk_mul_f32 v[150:151], v[8:9], v[8:9]
	v_add_f32_e32 v112, v112, v149
	v_add_f32_e32 v112, v112, v150
	v_pk_mul_f32 v[152:153], v[2:3], v[2:3]
	v_add_f32_e32 v112, v112, v151
	v_add_f32_e32 v112, v112, v152
	v_pk_fma_f32 v[70:71], v[14:15], v[74:75], v[70:71] op_sel_hi:[1,0,1] neg_lo:[0,0,1] neg_hi:[0,0,1]
	v_pk_fma_f32 v[72:73], v[16:17], v[74:75], v[72:73] op_sel_hi:[1,0,1] neg_lo:[0,0,1] neg_hi:[0,0,1]
	v_pk_fma_f32 v[6:7], v[12:13], v[74:75], v[144:145] op_sel_hi:[1,0,1] neg_lo:[0,0,1] neg_hi:[0,0,1]
	v_pk_mul_f32 v[74:75], v[10:11], v[10:11]
	v_add_f32_e32 v112, v112, v153
	v_add_f32_e32 v74, v112, v74
	v_pk_mul_f32 v[12:13], v[6:7], v[6:7]
	v_add_f32_e32 v74, v74, v75
	v_add_f32_e32 v12, v74, v12
	v_pk_mul_f32 v[92:93], v[70:71], v[70:71]
	v_add_f32_e32 v12, v12, v13
	v_add_f32_e32 v12, v12, v92
	v_pk_mul_f32 v[98:99], v[72:73], v[72:73]
	v_add_f32_e32 v12, v12, v93
	global_load_dwordx4 v[34:37], v163, s[10:11] offset:128
	global_load_dwordx4 v[14:17], v163, s[10:11] offset:160
	v_add_f32_e32 v12, v12, v98
	v_add_f32_e32 v74, v12, v99
	ds_bpermute_b32 v75, v170, v74
	v_lshl_add_u64 v[12:13], v[100:101], 0, v[0:1]
	global_load_dwordx4 v[42:45], v163, s[10:11] offset:192
	global_load_dwordx4 v[38:41], v163, s[10:11] offset:224
	global_load_dwordx4 v[46:49], v163, s[10:11] offset:256
	global_load_dwordx4 v[98:101], v163, s[10:11] offset:288
	global_load_dwordx4 v[112:115], v163, s[10:11] offset:320
	global_load_dwordx4 v[116:119], v163, s[10:11] offset:352
	s_waitcnt lgkmcnt(0)
	v_add_f32_e32 v0, v74, v75
	v_fmamk_f32 v0, v0, 0x3c000000, v189
	v_mul_f32_e32 v74, 0x4b800000, v0
	v_cmp_gt_f32_e32 vcc, s27, v0
	global_load_dwordx4 v[120:123], v163, s[10:11] offset:384
	global_load_dwordx4 v[124:127], v163, s[10:11] offset:416
	global_load_dwordx4 v[128:131], v163, s[10:11] offset:448
	global_load_dwordx4 v[132:135], v163, s[10:11] offset:480
	v_cndmask_b32_e32 v0, v0, v74, vcc
	v_rsq_f32_e32 v0, v0
	s_nop 0
	v_mul_f32_e32 v74, 0x45800000, v0
	v_cndmask_b32_e32 v0, v0, v74, vcc
	v_mul_f32_e32 v0, v177, v0
	s_waitcnt vmcnt(0)
; __device__ __forceinline__ unsigned cvtpk(float lo, float hi) { f32x2_t v = {lo, hi}; bf16x2_t b = __builtin_convertvector(v, bf16x2_t); return __builtin_bit_cast(unsigned, b); }
; template <bool DIFF> ...
;     ...
;             bf16_t* orow = Op + (size_t)(qr + l32) * opitch;
; #pragma unroll
;             for (int i = 0; i < 4; ++i)
; #pragma unroll
;                 for (int r4 = 0; r4 < 4; ++r4) { const int dv = i * 32 + r4 * 8 + hi * 4; const f32x4 gg = *(const f32x4*)(subg + dv); u32x2 w;
;                     w.x = cvtpk(o[i][4 * r4] * rstd * gg[0], o[i][4 * r4 + 1] * rstd * gg[1]); w.y = cvtpk(o[i][4 * r4 + 2] * rstd * gg[2], o[i][4 * r4 + 3] * rstd * gg[3]);
;                     *(u32x2*)(orow + dv) = w; }
	v_pk_mul_f32 v[94:95], v[94:95], v[0:1] op_sel_hi:[1,0]
	v_pk_mul_f32 v[90:91], v[90:91], v[0:1] op_sel_hi:[1,0]
	v_pk_mul_f32 v[104:105], v[104:105], v[0:1] op_sel_hi:[1,0]
	v_pk_mul_f32 v[96:97], v[96:97], v[0:1] op_sel_hi:[1,0]
	v_pk_mul_f32 v[94:95], v[94:95], v[66:67]
	v_pk_mul_f32 v[90:91], v[90:91], v[68:69]
	v_pk_mul_f32 v[104:105], v[104:105], v[50:51]
	v_pk_mul_f32 v[96:97], v[96:97], v[52:53]
	v_cvt_pk_bf16_f32 v66, v94, v95
	v_cvt_pk_bf16_f32 v67, v90, v91
	v_cvt_pk_bf16_f32 v68, v104, v105
	v_cvt_pk_bf16_f32 v69, v96, v97
	v_pk_mul_f32 v[108:109], v[108:109], v[0:1] op_sel_hi:[1,0]
	v_pk_mul_f32 v[102:103], v[102:103], v[0:1] op_sel_hi:[1,0]
	v_pk_mul_f32 v[110:111], v[110:111], v[0:1] op_sel_hi:[1,0]
	v_pk_mul_f32 v[106:107], v[106:107], v[0:1] op_sel_hi:[1,0]
	v_pk_mul_f32 v[108:109], v[108:109], v[58:59]
	v_pk_mul_f32 v[102:103], v[102:103], v[60:61]
	v_pk_mul_f32 v[110:111], v[110:111], v[54:55]
	v_pk_mul_f32 v[106:107], v[106:107], v[56:57]
	v_cvt_pk_bf16_f32 v58, v108, v109
	v_cvt_pk_bf16_f32 v59, v102, v103
	v_cvt_pk_bf16_f32 v60, v110, v111
	v_cvt_pk_bf16_f32 v61, v106, v107
	v_pk_mul_f32 v[64:65], v[64:65], v[0:1] op_sel_hi:[1,0]
	v_pk_mul_f32 v[62:63], v[62:63], v[0:1] op_sel_hi:[1,0]
	v_pk_mul_f32 v[80:81], v[80:81], v[0:1] op_sel_hi:[1,0]
	v_pk_mul_f32 v[76:77], v[76:77], v[0:1] op_sel_hi:[1,0]
	v_pk_mul_f32 v[64:65], v[64:65], v[34:35]
	v_pk_mul_f32 v[62:63], v[62:63], v[36:37]
	v_pk_mul_f32 v[80:81], v[80:81], v[14:15]
	v_pk_mul_f32 v[76:77], v[76:77], v[16:17]
	v_cvt_pk_bf16_f32 v34, v64, v65
	v_cvt_pk_bf16_f32 v35, v62, v63
	v_cvt_pk_bf16_f32 v36, v80, v81
	v_cvt_pk_bf16_f32 v37, v76, v77
	v_pk_mul_f32 v[82:83], v[82:83], v[0:1] op_sel_hi:[1,0]
	v_pk_mul_f32 v[78:79], v[78:79], v[0:1] op_sel_hi:[1,0]
	v_pk_mul_f32 v[86:87], v[86:87], v[0:1] op_sel_hi:[1,0]
	v_pk_mul_f32 v[84:85], v[84:85], v[0:1] op_sel_hi:[1,0]
	v_pk_mul_f32 v[82:83], v[82:83], v[42:43]
	v_pk_mul_f32 v[78:79], v[78:79], v[44:45]
	v_pk_mul_f32 v[86:87], v[86:87], v[38:39]
	v_pk_mul_f32 v[84:85], v[84:85], v[40:41]
	v_cvt_pk_bf16_f32 v42, v82, v83
	v_cvt_pk_bf16_f32 v43, v78, v79
	v_cvt_pk_bf16_f32 v44, v86, v87
	v_cvt_pk_bf16_f32 v45, v84, v85
	v_pk_mul_f32 v[88:89], v[88:89], v[0:1] op_sel_hi:[1,0]
	v_pk_mul_f32 v[20:21], v[20:21], v[0:1] op_sel_hi:[1,0]
	v_pk_mul_f32 v[24:25], v[24:25], v[0:1] op_sel_hi:[1,0]
	v_pk_mul_f32 v[18:19], v[18:19], v[0:1] op_sel_hi:[1,0]
	v_pk_mul_f32 v[88:89], v[88:89], v[46:47]
	v_pk_mul_f32 v[20:21], v[20:21], v[48:49]
	v_pk_mul_f32 v[24:25], v[24:25], v[98:99]
	v_pk_mul_f32 v[18:19], v[18:19], v[100:101]
	v_cvt_pk_bf16_f32 v46, v88, v89
	v_cvt_pk_bf16_f32 v47, v20, v21
	v_cvt_pk_bf16_f32 v48, v24, v25
	v_cvt_pk_bf16_f32 v49, v18, v19
	v_pk_mul_f32 v[28:29], v[28:29], v[0:1] op_sel_hi:[1,0]
	v_pk_mul_f32 v[22:23], v[22:23], v[0:1] op_sel_hi:[1,0]
	v_pk_mul_f32 v[30:31], v[30:31], v[0:1] op_sel_hi:[1,0]
	v_pk_mul_f32 v[26:27], v[26:27], v[0:1] op_sel_hi:[1,0]
	v_pk_mul_f32 v[28:29], v[28:29], v[112:113]
	v_pk_mul_f32 v[22:23], v[22:23], v[114:115]
	v_pk_mul_f32 v[30:31], v[30:31], v[116:117]
	v_pk_mul_f32 v[26:27], v[26:27], v[118:119]
	v_cvt_pk_bf16_f32 v112, v28, v29
	v_cvt_pk_bf16_f32 v113, v22, v23
	v_cvt_pk_bf16_f32 v114, v30, v31
	v_cvt_pk_bf16_f32 v115, v26, v27
	v_pk_mul_f32 v[32:33], v[32:33], v[0:1] op_sel_hi:[1,0]
	v_pk_mul_f32 v[4:5], v[4:5], v[0:1] op_sel_hi:[1,0]
	v_pk_mul_f32 v[8:9], v[8:9], v[0:1] op_sel_hi:[1,0]
	v_pk_mul_f32 v[2:3], v[2:3], v[0:1] op_sel_hi:[1,0]
	v_pk_mul_f32 v[32:33], v[32:33], v[120:121]
	v_pk_mul_f32 v[4:5], v[4:5], v[122:123]
	v_pk_mul_f32 v[8:9], v[8:9], v[124:125]
	v_pk_mul_f32 v[2:3], v[2:3], v[126:127]
	v_cvt_pk_bf16_f32 v120, v32, v33
	v_cvt_pk_bf16_f32 v121, v4, v5
	v_cvt_pk_bf16_f32 v122, v8, v9
	v_cvt_pk_bf16_f32 v123, v2, v3
	v_pk_mul_f32 v[10:11], v[10:11], v[0:1] op_sel_hi:[1,0]
	v_pk_mul_f32 v[6:7], v[6:7], v[0:1] op_sel_hi:[1,0]
	v_pk_mul_f32 v[70:71], v[70:71], v[0:1] op_sel_hi:[1,0]
	v_pk_mul_f32 v[72:73], v[72:73], v[0:1] op_sel_hi:[1,0]
	v_pk_mul_f32 v[10:11], v[10:11], v[128:129]
	v_pk_mul_f32 v[6:7], v[6:7], v[130:131]
	v_pk_mul_f32 v[70:71], v[70:71], v[132:133]
	v_pk_mul_f32 v[72:73], v[72:73], v[134:135]
	v_cvt_pk_bf16_f32 v128, v10, v11
	v_cvt_pk_bf16_f32 v129, v6, v7
	v_cvt_pk_bf16_f32 v130, v70, v71
	v_cvt_pk_bf16_f32 v131, v72, v73
	s_nop 1
	v_permlane32_swap_b32_e32 v66, v68
	v_permlane32_swap_b32_e32 v67, v69
	v_permlane32_swap_b32_e32 v58, v60
	v_permlane32_swap_b32_e32 v59, v61
	v_permlane32_swap_b32_e32 v34, v36
	v_permlane32_swap_b32_e32 v35, v37
	v_permlane32_swap_b32_e32 v42, v44
	v_permlane32_swap_b32_e32 v43, v45
	v_permlane32_swap_b32_e32 v46, v48
	v_permlane32_swap_b32_e32 v47, v49
	v_permlane32_swap_b32_e32 v112, v114
	v_permlane32_swap_b32_e32 v113, v115
	v_permlane32_swap_b32_e32 v120, v122
	v_permlane32_swap_b32_e32 v121, v123
	v_permlane32_swap_b32_e32 v128, v130
	v_permlane32_swap_b32_e32 v129, v131
	global_store_dwordx4 v[12:13], v[66:69], off
	global_store_dwordx4 v[12:13], v[58:61], off offset:32
	global_store_dwordx4 v[12:13], v[34:37], off offset:64
	global_store_dwordx4 v[12:13], v[42:45], off offset:96
	global_store_dwordx4 v[12:13], v[46:49], off offset:128
	global_store_dwordx4 v[12:13], v[112:115], off offset:160
	global_store_dwordx4 v[12:13], v[120:123], off offset:192
	global_store_dwordx4 v[12:13], v[128:131], off offset:224
	s_branch .LBB0_110
